# removed 12 dead S-tile phi copies (s_nop + 8 v_mov_b64 after each QK chain) from both attention loops
# speedup vs baseline: 1.0019x; 1.0019x over previous
.LBB0_372:
	s_add_i32 s8, s58, 33
	s_cmp_le_i32 s8, s57
	s_cselect_b64 s[8:9], -1, 0
	s_and_b64 s[8:9], s[8:9], s[6:7]
	v_cndmask_b32_e64 v32, 0, 1, s[8:9]
	v_cmp_ne_u32_e64 s[6:7], 1, v32
	s_nop 3
	s_andn2_b64 vcc, exec, s[8:9]
	s_cbranch_vccnz .LBB0_374
	v_add_u32_e32 v36, v159, v128
	ds_read_b128 v[32:35], v36 offset:9216
	ds_read_b128 v[112:115], v36 offset:9248
	ds_read_b128 v[116:119], v36 offset:9280
	ds_read_b128 v[120:123], v36 offset:9312
	s_waitcnt lgkmcnt(3)
	v_mfma_f32_32x32x16_bf16 v[32:47], v[32:35], v[72:75], 0
	s_waitcnt lgkmcnt(2)
	v_mfma_f32_32x32x16_bf16 v[32:47], v[112:115], v[64:67], v[32:47]
	s_waitcnt lgkmcnt(1)
	v_mfma_f32_32x32x16_bf16 v[32:47], v[116:119], v[68:71], v[32:47]
	s_waitcnt lgkmcnt(0)
	v_mfma_f32_32x32x16_bf16 v[32:47], v[120:123], v[76:79], v[32:47]

.LBB0_380:
	s_cmp_lt_i32 s58, s57
	s_cselect_b64 s[0:1], -1, 0
	s_cmp_eq_u32 s17, 0
	s_cselect_b64 s[8:9], -1, 0
	s_and_b64 s[0:1], s[0:1], s[8:9]
	v_cndmask_b32_e64 v48, 0, 1, s[0:1]
	v_cmp_ne_u32_e64 s[8:9], 1, v48
	s_nop 3
	s_andn2_b64 vcc, exec, s[0:1]
	s_cbranch_vccnz .LBB0_382
	v_add_u32_e32 v52, v159, v128
	ds_read_b128 v[48:51], v52 offset:4608
	ds_read_b128 v[112:115], v52 offset:4640
	ds_read_b128 v[116:119], v52 offset:4672
	ds_read_b128 v[120:123], v52 offset:4704
	s_waitcnt lgkmcnt(3)
	v_mfma_f32_32x32x16_bf16 v[48:63], v[48:51], v[72:75], 0
	s_waitcnt lgkmcnt(2)
	v_mfma_f32_32x32x16_bf16 v[48:63], v[112:115], v[64:67], v[48:63]
	s_waitcnt lgkmcnt(1)
	v_mfma_f32_32x32x16_bf16 v[48:63], v[116:119], v[68:71], v[48:63]
	s_waitcnt lgkmcnt(0)
	v_mfma_f32_32x32x16_bf16 v[48:63], v[120:123], v[76:79], v[48:63]

.LBB0_388:
	s_cmp_le_i32 s58, s61
	s_cselect_b64 s[0:1], -1, 0
	s_cmp_eq_u32 s17, 0
	s_cselect_b64 s[6:7], -1, 0
	s_and_b64 s[0:1], s[0:1], s[6:7]
	v_cndmask_b32_e64 v32, 0, 1, s[0:1]
	v_cmp_ne_u32_e64 s[6:7], 1, v32
	s_nop 3
	s_andn2_b64 vcc, exec, s[0:1]
	s_cbranch_vccz .LBB0_396
	s_and_b64 vcc, exec, s[8:9]
	s_cbranch_vccz .LBB0_397

.LBB0_412:
	s_add_i32 s8, s58, 0xffffffa1
	s_cmp_le_i32 s8, s57
	s_cselect_b64 s[8:9], -1, 0
	s_and_b64 s[8:9], s[8:9], s[6:7]
	v_cndmask_b32_e64 v32, 0, 1, s[8:9]
	v_cmp_ne_u32_e64 s[6:7], 1, v32
	s_nop 3
	s_andn2_b64 vcc, exec, s[8:9]
	s_cbranch_vccnz .LBB0_414
	ds_read_b128 v[32:35], v169 offset:9216
	ds_read_b128 v[112:115], v169 offset:9248
	ds_read_b128 v[116:119], v169 offset:9280
	ds_read_b128 v[120:123], v169 offset:9312
	s_waitcnt lgkmcnt(3)
	v_mfma_f32_32x32x16_bf16 v[32:47], v[32:35], v[72:75], 0
	s_waitcnt lgkmcnt(2)
	v_mfma_f32_32x32x16_bf16 v[32:47], v[112:115], v[64:67], v[32:47]
	s_waitcnt lgkmcnt(1)
	v_mfma_f32_32x32x16_bf16 v[32:47], v[116:119], v[68:71], v[32:47]
	s_waitcnt lgkmcnt(0)
	v_mfma_f32_32x32x16_bf16 v[32:47], v[120:123], v[76:79], v[32:47]

.LBB0_420:
	s_add_i32 s63, s58, 0xffffff80
	s_cmp_lt_i32 s63, s57
	s_cselect_b64 s[0:1], -1, 0
	s_cmp_eq_u32 s17, 0
	s_cselect_b64 s[8:9], -1, 0
	s_and_b64 s[0:1], s[0:1], s[8:9]
	v_cndmask_b32_e64 v48, 0, 1, s[0:1]
	v_cmp_ne_u32_e64 s[8:9], 1, v48
	s_nop 3
	s_andn2_b64 vcc, exec, s[0:1]
	s_cbranch_vccnz .LBB0_422
	ds_read_b128 v[48:51], v169 offset:4608
	ds_read_b128 v[112:115], v169 offset:4640
	ds_read_b128 v[116:119], v169 offset:4672
	ds_read_b128 v[120:123], v169 offset:4704
	s_waitcnt lgkmcnt(3)
	v_mfma_f32_32x32x16_bf16 v[48:63], v[48:51], v[72:75], 0
	s_waitcnt lgkmcnt(2)
	v_mfma_f32_32x32x16_bf16 v[48:63], v[112:115], v[64:67], v[48:63]
	s_waitcnt lgkmcnt(1)
	v_mfma_f32_32x32x16_bf16 v[48:63], v[116:119], v[68:71], v[48:63]
	s_waitcnt lgkmcnt(0)
	v_mfma_f32_32x32x16_bf16 v[48:63], v[120:123], v[76:79], v[48:63]

.LBB0_428:
	s_cmp_le_i32 s63, s61
	s_cselect_b64 s[0:1], -1, 0
	s_cmp_eq_u32 s17, 0
	s_cselect_b64 s[6:7], -1, 0
	s_and_b64 s[0:1], s[0:1], s[6:7]
	v_cndmask_b32_e64 v32, 0, 1, s[0:1]
	v_cmp_ne_u32_e64 s[6:7], 1, v32
	s_nop 3
	s_andn2_b64 vcc, exec, s[0:1]
	s_cbranch_vccz .LBB0_431
	s_and_b64 vcc, exec, s[8:9]
	s_cbranch_vccz .LBB0_432

.LBB0_451:
	s_or_b32 s17, s59, 33
	s_cmp_le_i32 s17, s56
	s_nop 3
	s_cselect_b64 s[0:1], -1, 0
	s_cmp_gt_i32 s17, s56
	s_cbranch_scc1 .LBB0_453
	ds_read_b128 v[32:35], v202 offset:9216
	ds_read_b128 v[112:115], v202 offset:9248
	ds_read_b128 v[116:119], v202 offset:9280
	ds_read_b128 v[120:123], v202 offset:9312
	s_waitcnt lgkmcnt(3)
	v_mfma_f32_32x32x16_bf16 v[32:47], v[32:35], v[64:67], 0
	s_waitcnt lgkmcnt(2)
	v_mfma_f32_32x32x16_bf16 v[32:47], v[112:115], v[68:71], v[32:47]
	s_waitcnt lgkmcnt(1)
	v_mfma_f32_32x32x16_bf16 v[32:47], v[116:119], v[72:75], v[32:47]
	s_waitcnt lgkmcnt(0)
	v_mfma_f32_32x32x16_bf16 v[32:47], v[120:123], v[76:79], v[32:47]

.LBB0_460:
	s_cmp_gt_i32 s56, s59
	s_nop 3
	s_cselect_b64 s[42:43], -1, 0
	s_cmp_le_i32 s56, s59
	s_cbranch_scc1 .LBB0_462
	ds_read_b128 v[48:51], v202 offset:4608
	ds_read_b128 v[112:115], v202 offset:4640
	ds_read_b128 v[116:119], v202 offset:4672
	ds_read_b128 v[120:123], v202 offset:4704
	s_waitcnt lgkmcnt(3)
	v_mfma_f32_32x32x16_bf16 v[48:63], v[48:51], v[64:67], 0
	s_waitcnt lgkmcnt(2)
	v_mfma_f32_32x32x16_bf16 v[48:63], v[112:115], v[68:71], v[48:63]
	s_waitcnt lgkmcnt(1)
	v_mfma_f32_32x32x16_bf16 v[48:63], v[116:119], v[72:75], v[48:63]
	s_waitcnt lgkmcnt(0)
	v_mfma_f32_32x32x16_bf16 v[48:63], v[120:123], v[76:79], v[48:63]

.LBB0_469:
	s_cmp_le_i32 s59, s58
	s_nop 3
	s_cselect_b64 s[0:1], -1, 0
	s_cmp_gt_i32 s59, s58
	s_cbranch_scc1 .LBB0_471
	ds_read_b128 v[32:35], v202
	ds_read_b128 v[112:115], v202 offset:32
	ds_read_b128 v[116:119], v202 offset:64
	ds_read_b128 v[120:123], v202 offset:96
	s_waitcnt lgkmcnt(3)
	v_mfma_f32_32x32x16_bf16 v[32:47], v[32:35], v[64:67], 0
	s_waitcnt lgkmcnt(2)
	v_mfma_f32_32x32x16_bf16 v[32:47], v[112:115], v[68:71], v[32:47]
	s_waitcnt lgkmcnt(1)
	v_mfma_f32_32x32x16_bf16 v[32:47], v[116:119], v[72:75], v[32:47]
	s_waitcnt lgkmcnt(0)
	v_mfma_f32_32x32x16_bf16 v[32:47], v[120:123], v[76:79], v[32:47]

.LBB0_488:
	s_addk_i32 s59, 0xff80
	s_or_b32 s17, s59, 33
	s_cmp_le_i32 s17, s56
	s_nop 3
	s_cselect_b64 s[0:1], -1, 0
	s_cmp_gt_i32 s17, s56
	s_cbranch_scc1 .LBB0_490
	ds_read_b128 v[32:35], v202 offset:9216
	ds_read_b128 v[112:115], v202 offset:9248
	ds_read_b128 v[116:119], v202 offset:9280
	ds_read_b128 v[120:123], v202 offset:9312
	s_waitcnt lgkmcnt(3)
	v_mfma_f32_32x32x16_bf16 v[32:47], v[32:35], v[64:67], 0
	s_waitcnt lgkmcnt(2)
	v_mfma_f32_32x32x16_bf16 v[32:47], v[112:115], v[68:71], v[32:47]
	s_waitcnt lgkmcnt(1)
	v_mfma_f32_32x32x16_bf16 v[32:47], v[116:119], v[72:75], v[32:47]
	s_waitcnt lgkmcnt(0)
	v_mfma_f32_32x32x16_bf16 v[32:47], v[120:123], v[76:79], v[32:47]
